# v63 + grid-barrier polling loops use s_sleep 0 instead of s_sleep 1 (tighter polling)
# baseline (speedup 1.0000x reference)
; __device__ __forceinline__ unsigned xb_ld(unsigned* p)              { return __hip_atomic_load(p, __ATOMIC_RELAXED, __HIP_MEMORY_SCOPE_AGENT); }
; __device__ __forceinline__ void xcd_barrier_complete(unsigned* bar, unsigned x, unsigned& nloc, unsigned& nx) {
;     const unsigned G = gridDim.x * gridDim.y * gridDim.z;
;     unsigned sum, cnt, mine, sp = 0u;
;     for (;;) {
;         sum = 0u; cnt = 0u; mine = 0u;
; #pragma unroll
;         for (unsigned j = 0; j < 16; ++j) { const unsigned c = xb_ld(&bar[XB_XCNT(j)]); sum += c; cnt += (c > 0u) ? 1u : 0u; mine = (j == x) ? c : mine; }
;         if (sum == G) break;
;         __builtin_amdgcn_s_sleep(1);
;         if ((++sp & 255u) == 0u) { if (xb_ld(&bar[XB_TMO])) break; if (sp > XB_SPIN_CAP) { atomicAdd(&bar[XB_TMO], 1u); break; } }
;     }
.LBB0_107:
	global_load_dword v17, v18, s[4:5] offset:1024 sc1
	global_load_dword v1, v18, s[4:5] offset:1280 sc1
	global_load_dword v2, v18, s[4:5] offset:1536 sc1
	global_load_dword v3, v18, s[4:5] offset:1792 sc1
	global_load_dword v4, v18, s[4:5] offset:2048 sc1
	global_load_dword v5, v18, s[4:5] offset:2304 sc1
	global_load_dword v6, v18, s[4:5] offset:2560 sc1
	global_load_dword v7, v18, s[4:5] offset:2816 sc1
	global_load_dword v9, v18, s[4:5] offset:3072 sc1
	global_load_dword v10, v18, s[4:5] offset:3328 sc1
	global_load_dword v11, v18, s[4:5] offset:3584 sc1
	global_load_dword v12, v18, s[4:5] offset:3840 sc1
	global_load_dword v13, v18, s[6:7] sc1
	global_load_dword v14, v18, s[8:9] sc1
	global_load_dword v15, v18, s[10:11] sc1
	global_load_dword v16, v18, s[12:13] sc1
	s_mov_b64 s[14:15], -1
	s_mov_b64 s[16:17], -1
	s_waitcnt vmcnt(14)
	v_add_u32_e32 v0, v1, v17
	s_waitcnt vmcnt(13)
	v_add_u32_e32 v0, v0, v2
	s_waitcnt vmcnt(12)
	v_add_u32_e32 v0, v0, v3
	s_waitcnt vmcnt(11)
	v_add_u32_e32 v0, v0, v4
	s_waitcnt vmcnt(10)
	v_add_u32_e32 v0, v0, v5
	s_waitcnt vmcnt(9)
	v_add_u32_e32 v0, v0, v6
	s_waitcnt vmcnt(8)
	v_add_u32_e32 v0, v0, v7
	s_waitcnt vmcnt(7)
	v_add_u32_e32 v0, v0, v9
	s_waitcnt vmcnt(6)
	v_add_u32_e32 v0, v0, v10
	s_waitcnt vmcnt(5)
	v_add_u32_e32 v0, v0, v11
	s_waitcnt vmcnt(4)
	v_add_u32_e32 v0, v0, v12
	s_waitcnt vmcnt(3)
	v_add_u32_e32 v0, v0, v13
	s_waitcnt vmcnt(2)
	v_add_u32_e32 v0, v0, v14
	s_waitcnt vmcnt(1)
	v_add_u32_e32 v0, v0, v15
	s_waitcnt vmcnt(0)
	v_add_u32_e32 v0, v0, v16
	v_cmp_eq_u32_e32 vcc, s1, v0
	s_cbranch_vccnz .LBB0_106
	s_and_b32 s14, s18, 0xff
	s_cmp_eq_u32 s14, 0
	s_mov_b64 s[14:15], -1
	s_mov_b64 s[20:21], -1
	s_sleep 0
	s_cbranch_scc1 .LBB0_111
	s_and_b64 vcc, exec, s[20:21]
	s_cbranch_vccz .LBB0_106

.LBB0_125:
	s_and_b32 s1, s0, 0xff
	s_mov_b64 s[20:21], -1
	s_cmp_lg_u32 s1, 0
	s_mov_b64 s[24:25], -1
	s_sleep 0
	s_cbranch_scc0 .LBB0_128
	s_and_b64 vcc, exec, s[24:25]
	s_cbranch_vccz .LBB0_124

.LBB0_142:
	s_and_b32 s1, s0, 0xff
	s_cmp_lg_u32 s1, 0
	s_mov_b64 s[24:25], -1
	s_sleep 0
	s_cbranch_scc0 .LBB0_145
	s_mov_b64 s[26:27], -1
	s_and_b64 vcc, exec, s[24:25]
	s_cbranch_vccz .LBB0_141

; __device__ __forceinline__ unsigned xb_ld(unsigned* p)              { return __hip_atomic_load(p, __ATOMIC_RELAXED, __HIP_MEMORY_SCOPE_AGENT); }
; __device__ __forceinline__ void xcd_barrier_complete(unsigned* bar, unsigned x, unsigned& nloc, unsigned& nx) {
;     const unsigned G = gridDim.x * gridDim.y * gridDim.z;
;     unsigned sum, cnt, mine, sp = 0u;
;     for (;;) {
;         sum = 0u; cnt = 0u; mine = 0u;
; #pragma unroll
;         for (unsigned j = 0; j < 16; ++j) { const unsigned c = xb_ld(&bar[XB_XCNT(j)]); sum += c; cnt += (c > 0u) ? 1u : 0u; mine = (j == x) ? c : mine; }
;         if (sum == G) break;
;         __builtin_amdgcn_s_sleep(1);
;         if ((++sp & 255u) == 0u) { if (xb_ld(&bar[XB_TMO])) break; if (sp > XB_SPIN_CAP) { atomicAdd(&bar[XB_TMO], 1u); break; } }
;     }
.LBB0_190:
	global_load_dword v18, v5, s[4:5] offset:1024 sc1
	global_load_dword v2, v5, s[4:5] offset:1280 sc1
	global_load_dword v3, v5, s[4:5] offset:1536 sc1
	global_load_dword v4, v5, s[4:5] offset:1792 sc1
	global_load_dword v6, v5, s[4:5] offset:2048 sc1
	global_load_dword v7, v5, s[4:5] offset:2304 sc1
	global_load_dword v8, v5, s[4:5] offset:2560 sc1
	global_load_dword v9, v5, s[4:5] offset:2816 sc1
	global_load_dword v10, v5, s[4:5] offset:3072 sc1
	global_load_dword v11, v5, s[4:5] offset:3328 sc1
	global_load_dword v12, v5, s[4:5] offset:3584 sc1
	global_load_dword v13, v5, s[4:5] offset:3840 sc1
	global_load_dword v14, v5, s[6:7] sc1
	global_load_dword v15, v5, s[8:9] sc1
	global_load_dword v16, v5, s[10:11] sc1
	global_load_dword v17, v5, s[12:13] sc1
	s_mov_b64 s[14:15], -1
	s_mov_b64 s[16:17], -1
	s_waitcnt vmcnt(14)
	v_add_u32_e32 v19, v2, v18
	s_waitcnt vmcnt(13)
	v_add_u32_e32 v19, v19, v3
	s_waitcnt vmcnt(12)
	v_add_u32_e32 v19, v19, v4
	s_waitcnt vmcnt(11)
	v_add_u32_e32 v19, v19, v6
	s_waitcnt vmcnt(10)
	v_add_u32_e32 v19, v19, v7
	s_waitcnt vmcnt(9)
	v_add_u32_e32 v19, v19, v8
	s_waitcnt vmcnt(8)
	v_add_u32_e32 v19, v19, v9
	s_waitcnt vmcnt(7)
	v_add_u32_e32 v19, v19, v10
	s_waitcnt vmcnt(6)
	v_add_u32_e32 v19, v19, v11
	s_waitcnt vmcnt(5)
	v_add_u32_e32 v19, v19, v12
	s_waitcnt vmcnt(4)
	v_add_u32_e32 v19, v19, v13
	s_waitcnt vmcnt(3)
	v_add_u32_e32 v19, v19, v14
	s_waitcnt vmcnt(2)
	v_add_u32_e32 v19, v19, v15
	s_waitcnt vmcnt(1)
	v_add_u32_e32 v19, v19, v16
	s_waitcnt vmcnt(0)
	v_add_u32_e32 v19, v19, v17
	v_cmp_eq_u32_e32 vcc, s23, v19
	s_cbranch_vccnz .LBB0_189
	s_and_b32 s14, s24, 0xff
	s_cmp_eq_u32 s14, 0
	s_mov_b64 s[14:15], -1
	s_mov_b64 s[20:21], -1
	s_sleep 0
	s_cbranch_scc1 .LBB0_194
	s_and_b64 vcc, exec, s[20:21]
	s_cbranch_vccz .LBB0_189

.LBB0_208:
	s_and_b32 s22, s26, 0xff
	s_mov_b64 s[20:21], -1
	s_cmp_lg_u32 s22, 0
	s_mov_b64 s[24:25], -1
	s_sleep 0
	s_cbranch_scc0 .LBB0_211
	s_and_b64 vcc, exec, s[24:25]
	s_cbranch_vccz .LBB0_207

.LBB0_225:
	s_and_b32 s24, s30, 0xff
	s_mov_b64 s[22:23], -1
	s_cmp_lg_u32 s24, 0
	s_mov_b64 s[26:27], -1
	s_sleep 0
	s_cbranch_scc0 .LBB0_228
	s_and_b64 vcc, exec, s[26:27]
	s_cbranch_vccz .LBB0_224

; __device__ __forceinline__ unsigned xb_ld(unsigned* p)              { return __hip_atomic_load(p, __ATOMIC_RELAXED, __HIP_MEMORY_SCOPE_AGENT); }
; __device__ __forceinline__ void xcd_barrier_complete(unsigned* bar, unsigned x, unsigned& nloc, unsigned& nx) {
;     const unsigned G = gridDim.x * gridDim.y * gridDim.z;
;     unsigned sum, cnt, mine, sp = 0u;
;     for (;;) {
;         sum = 0u; cnt = 0u; mine = 0u;
; #pragma unroll
;         for (unsigned j = 0; j < 16; ++j) { const unsigned c = xb_ld(&bar[XB_XCNT(j)]); sum += c; cnt += (c > 0u) ? 1u : 0u; mine = (j == x) ? c : mine; }
;         if (sum == G) break;
;         __builtin_amdgcn_s_sleep(1);
;         if ((++sp & 255u) == 0u) { if (xb_ld(&bar[XB_TMO])) break; if (sp > XB_SPIN_CAP) { atomicAdd(&bar[XB_TMO], 1u); break; } }
;     }
.LBB0_766:
	global_load_dword v18, v5, s[4:5] offset:1024 sc1
	global_load_dword v2, v5, s[4:5] offset:1280 sc1
	global_load_dword v3, v5, s[4:5] offset:1536 sc1
	global_load_dword v4, v5, s[4:5] offset:1792 sc1
	global_load_dword v6, v5, s[4:5] offset:2048 sc1
	global_load_dword v7, v5, s[4:5] offset:2304 sc1
	global_load_dword v8, v5, s[4:5] offset:2560 sc1
	global_load_dword v9, v5, s[4:5] offset:2816 sc1
	global_load_dword v10, v5, s[4:5] offset:3072 sc1
	global_load_dword v11, v5, s[4:5] offset:3328 sc1
	global_load_dword v12, v5, s[4:5] offset:3584 sc1
	global_load_dword v13, v5, s[4:5] offset:3840 sc1
	global_load_dword v14, v5, s[6:7] sc1
	global_load_dword v15, v5, s[8:9] sc1
	global_load_dword v16, v5, s[10:11] sc1
	global_load_dword v17, v5, s[12:13] sc1
	s_mov_b64 s[14:15], -1
	s_mov_b64 s[16:17], -1
	s_waitcnt vmcnt(14)
	v_add_u32_e32 v19, v2, v18
	s_waitcnt vmcnt(13)
	v_add_u32_e32 v19, v19, v3
	s_waitcnt vmcnt(12)
	v_add_u32_e32 v19, v19, v4
	s_waitcnt vmcnt(11)
	v_add_u32_e32 v19, v19, v6
	s_waitcnt vmcnt(10)
	v_add_u32_e32 v19, v19, v7
	s_waitcnt vmcnt(9)
	v_add_u32_e32 v19, v19, v8
	s_waitcnt vmcnt(8)
	v_add_u32_e32 v19, v19, v9
	s_waitcnt vmcnt(7)
	v_add_u32_e32 v19, v19, v10
	s_waitcnt vmcnt(6)
	v_add_u32_e32 v19, v19, v11
	s_waitcnt vmcnt(5)
	v_add_u32_e32 v19, v19, v12
	s_waitcnt vmcnt(4)
	v_add_u32_e32 v19, v19, v13
	s_waitcnt vmcnt(3)
	v_add_u32_e32 v19, v19, v14
	s_waitcnt vmcnt(2)
	v_add_u32_e32 v19, v19, v15
	s_waitcnt vmcnt(1)
	v_add_u32_e32 v19, v19, v16
	s_waitcnt vmcnt(0)
	v_add_u32_e32 v19, v19, v17
	v_cmp_eq_u32_e32 vcc, s25, v19
	s_cbranch_vccnz .LBB0_765
	s_and_b32 s14, s26, 0xff
	s_cmp_eq_u32 s14, 0
	s_mov_b64 s[14:15], -1
	s_mov_b64 s[20:21], -1
	s_sleep 0
	s_cbranch_scc1 .LBB0_770
	s_and_b64 vcc, exec, s[20:21]
	s_cbranch_vccz .LBB0_765

.LBB0_784:
	s_and_b32 s24, s30, 0xff
	s_mov_b64 s[20:21], -1
	s_cmp_lg_u32 s24, 0
	s_mov_b64 s[26:27], -1
	s_sleep 0
	s_cbranch_scc0 .LBB0_787
	s_and_b64 vcc, exec, s[26:27]
	s_cbranch_vccz .LBB0_783

.LBB0_801:
	s_and_b32 s26, s34, 0xff
	s_mov_b64 s[24:25], -1
	s_cmp_lg_u32 s26, 0
	s_mov_b64 s[30:31], -1
	s_sleep 0
	s_cbranch_scc0 .LBB0_804
	s_and_b64 vcc, exec, s[30:31]
	s_cbranch_vccz .LBB0_800

.LBB0_1036:
	s_and_b32 s22, s27, 0xff
	s_mov_b64 s[20:21], -1
	s_cmp_lg_u32 s22, 0
	s_mov_b64 s[24:25], -1
	s_sleep 0
	s_cbranch_scc0 .LBB0_1039
	s_and_b64 vcc, exec, s[24:25]
	s_cbranch_vccz .LBB0_1035
